# code placement check: all GEMM MFMA segment heads at byte phase 4 mod 8 (17 s_nop pads in load segments)
# baseline (speedup 1.0000x reference)
.LBB0_200:
	s_nop 0
	s_ashr_i32 s23, s22, 31
	s_lshl_b64 s[6:7], s[22:23], 20
	s_add_u32 s6, s29, s6
	s_addc_u32 s7, s34, s7
	s_ashr_i32 s25, s24, 31
	s_lshl_b64 s[36:37], s[24:25], 1
	s_add_u32 s6, s6, s36
	s_addc_u32 s7, s7, s37
	s_and_b64 s[44:45], s[52:53], exec
	s_cselect_b32 s23, s7, s43
	s_cselect_b32 s25, s6, s42
	s_ashr_i32 s27, s26, 31
	s_lshl_b64 s[44:45], s[26:27], 20
	s_add_u32 s27, s35, s44
	s_addc_u32 s41, s54, s45
	s_add_u32 s36, s27, s36
	s_addc_u32 s37, s41, s37
	s_and_b64 s[44:45], s[52:53], exec
	s_cselect_b32 s27, s37, s51
	s_cselect_b32 s41, s36, s50
	s_add_i32 s44, s33, -2
	s_add_u32 s42, s42, 0x80080
	s_addc_u32 s43, s43, 0
	s_add_u32 s45, s50, 0x100
	s_addc_u32 s58, s51, 0
	s_mov_b32 s50, 0
	v_add_u32_e32 v253, 0x10000, v147
	s_add_i32 s59, s50, 2
	s_add_u32 s51, s42, 0xfff80080
	s_addc_u32 s52, s43, -1
	s_add_i32 s70, 0, 0x10000
	s_cmp_eq_u32 s44, s50
	s_cselect_b32 s53, s23, s52
	s_cselect_b32 s52, s25, s51
	s_cselect_b32 s51, s27, s58
	s_cselect_b32 s50, s41, s45
	s_add_i32 s74, 0, 0x14000
	ds_read_b128 v[150:153], v253
	ds_read_b128 v[154:157], v253 offset:1024
	ds_read_b128 v[158:161], v253 offset:2048
	ds_read_b128 v[162:165], v253 offset:3072
	ds_read_b128 v[166:169], v253 offset:16384
	ds_read_b128 v[170:173], v253 offset:17408
	ds_read_b128 v[174:177], v253 offset:18432
	ds_read_b128 v[178:181], v253 offset:19456
	s_add_i32 m0, s31, 0xc000
	ds_read_b128 v[182:185], v149
	ds_read_b128 v[186:189], v149 offset:1024
	ds_read_b128 v[190:193], v149 offset:2048
	ds_read_b128 v[204:207], v149 offset:3072
	ds_read_b128 v[208:211], v149 offset:4096
	ds_read_b128 v[212:215], v149 offset:5120
	ds_read_b128 v[216:219], v149 offset:6144
	ds_read_b128 v[220:223], v149 offset:7168
	global_load_lds_dwordx4 v140, s[42:43]
	s_add_i32 m0, s31, 0xe000
	s_nop 0
	global_load_lds_dwordx4 v142, s[42:43]
	s_waitcnt vmcnt(8)
	s_waitcnt lgkmcnt(0)
	s_barrier
	s_setprio 1
	s_waitcnt lgkmcnt(0)
	v_mfma_f32_16x16x32_bf16 v[126:129], v[150:153], v[182:185], 0
	v_mfma_f32_16x16x32_bf16 v[122:125], v[158:161], v[182:185], 0
	v_mfma_f32_16x16x32_bf16 v[114:117], v[150:153], v[190:193], 0
	v_mfma_f32_16x16x32_bf16 v[106:109], v[158:161], v[190:193], 0
	v_mfma_f32_16x16x32_bf16 v[98:101], v[150:153], v[208:211], 0
	v_mfma_f32_16x16x32_bf16 v[90:93], v[158:161], v[208:211], 0
	v_mfma_f32_16x16x32_bf16 v[82:85], v[150:153], v[216:219], 0
	v_mfma_f32_16x16x32_bf16 v[74:77], v[158:161], v[216:219], 0
	v_mfma_f32_16x16x32_bf16 v[126:129], v[154:157], v[186:189], v[126:129]
	v_mfma_f32_16x16x32_bf16 v[122:125], v[162:165], v[186:189], v[122:125]
	v_mfma_f32_16x16x32_bf16 v[114:117], v[154:157], v[204:207], v[114:117]
	v_mfma_f32_16x16x32_bf16 v[106:109], v[162:165], v[204:207], v[106:109]
	v_mfma_f32_16x16x32_bf16 v[98:101], v[154:157], v[212:215], v[98:101]
	v_mfma_f32_16x16x32_bf16 v[90:93], v[162:165], v[212:215], v[90:93]
	v_mfma_f32_16x16x32_bf16 v[82:85], v[154:157], v[220:223], v[82:85]
	v_mfma_f32_16x16x32_bf16 v[74:77], v[162:165], v[220:223], v[74:77]
	s_setprio 0
	s_setprio 1
	v_mfma_f32_16x16x32_bf16 v[118:121], v[166:169], v[182:185], 0
	v_mfma_f32_16x16x32_bf16 v[110:113], v[174:177], v[182:185], 0
	v_mfma_f32_16x16x32_bf16 v[102:105], v[166:169], v[190:193], 0
	v_mfma_f32_16x16x32_bf16 v[94:97], v[174:177], v[190:193], 0
	v_mfma_f32_16x16x32_bf16 v[86:89], v[166:169], v[208:211], 0
	v_mfma_f32_16x16x32_bf16 v[78:81], v[174:177], v[208:211], 0
	v_mfma_f32_16x16x32_bf16 v[70:73], v[166:169], v[216:219], 0
	v_mfma_f32_16x16x32_bf16 v[66:69], v[174:177], v[216:219], 0
	v_mfma_f32_16x16x32_bf16 v[118:121], v[170:173], v[186:189], v[118:121]
	v_mfma_f32_16x16x32_bf16 v[110:113], v[178:181], v[186:189], v[110:113]
	v_mfma_f32_16x16x32_bf16 v[102:105], v[170:173], v[204:207], v[102:105]
	v_mfma_f32_16x16x32_bf16 v[94:97], v[178:181], v[204:207], v[94:97]
	v_mfma_f32_16x16x32_bf16 v[86:89], v[170:173], v[212:215], v[86:89]
	v_mfma_f32_16x16x32_bf16 v[78:81], v[178:181], v[212:215], v[78:81]
	v_mfma_f32_16x16x32_bf16 v[70:73], v[170:173], v[220:223], v[70:73]
	v_mfma_f32_16x16x32_bf16 v[66:69], v[178:181], v[220:223], v[66:69]
	s_setprio 0
	s_barrier
	s_add_i32 s70, s70, s55
	s_mov_b32 m0, s70
	ds_read_b128 v[182:185], v149 offset:16384
	ds_read_b128 v[186:189], v149 offset:17408
	ds_read_b128 v[190:193], v149 offset:18432
	ds_read_b128 v[204:207], v149 offset:19456
	ds_read_b128 v[208:211], v149 offset:20480
	ds_read_b128 v[212:215], v149 offset:21504
	ds_read_b128 v[216:219], v149 offset:22528
	ds_read_b128 v[220:223], v149 offset:23552
	global_load_lds_dwordx4 v0, s[50:51]
	s_add_i32 m0, s70, 0x2000
	s_add_u32 s70, s50, 0x80000
	s_addc_u32 s71, s51, 0
	s_add_i32 s74, s74, s55
	global_load_lds_dwordx4 v134, s[50:51]
	s_mov_b32 m0, s74
	s_nop 0
	global_load_lds_dwordx4 v0, s[70:71]
	s_add_i32 m0, s74, 0x2000
	s_nop 0
	global_load_lds_dwordx4 v134, s[70:71]
	s_mov_b32 m0, s31
	s_nop 0
	global_load_lds_dwordx4 v130, s[52:53]
	s_mov_b32 m0, s39
	s_nop 0
	global_load_lds_dwordx4 v132, s[52:53]
	s_waitcnt vmcnt(8)
	s_waitcnt lgkmcnt(0)
	s_barrier
	s_setprio 1
	s_waitcnt lgkmcnt(0)
	v_mfma_f32_16x16x32_bf16 v[62:65], v[150:153], v[182:185], 0
	v_mfma_f32_16x16x32_bf16 v[58:61], v[158:161], v[182:185], 0
	v_mfma_f32_16x16x32_bf16 v[50:53], v[150:153], v[190:193], 0
	v_mfma_f32_16x16x32_bf16 v[42:45], v[158:161], v[190:193], 0
	v_mfma_f32_16x16x32_bf16 v[34:37], v[150:153], v[208:211], 0
	v_mfma_f32_16x16x32_bf16 v[26:29], v[158:161], v[208:211], 0
	v_mfma_f32_16x16x32_bf16 v[18:21], v[150:153], v[216:219], 0
	v_mfma_f32_16x16x32_bf16 v[10:13], v[158:161], v[216:219], 0
	v_mfma_f32_16x16x32_bf16 v[62:65], v[154:157], v[186:189], v[62:65]
	v_mfma_f32_16x16x32_bf16 v[58:61], v[162:165], v[186:189], v[58:61]
	v_mfma_f32_16x16x32_bf16 v[50:53], v[154:157], v[204:207], v[50:53]
	v_mfma_f32_16x16x32_bf16 v[42:45], v[162:165], v[204:207], v[42:45]
	v_mfma_f32_16x16x32_bf16 v[34:37], v[154:157], v[212:215], v[34:37]
	v_mfma_f32_16x16x32_bf16 v[26:29], v[162:165], v[212:215], v[26:29]
	v_mfma_f32_16x16x32_bf16 v[18:21], v[154:157], v[220:223], v[18:21]
	v_mfma_f32_16x16x32_bf16 v[10:13], v[162:165], v[220:223], v[10:13]
	s_setprio 0
	s_setprio 1
	v_mfma_f32_16x16x32_bf16 v[54:57], v[166:169], v[182:185], 0
	v_mfma_f32_16x16x32_bf16 v[46:49], v[174:177], v[182:185], 0
	v_mfma_f32_16x16x32_bf16 v[38:41], v[166:169], v[190:193], 0
	v_mfma_f32_16x16x32_bf16 v[30:33], v[174:177], v[190:193], 0
	v_mfma_f32_16x16x32_bf16 v[22:25], v[166:169], v[208:211], 0
	v_mfma_f32_16x16x32_bf16 v[14:17], v[174:177], v[208:211], 0
	v_mfma_f32_16x16x32_bf16 v[6:9], v[166:169], v[216:219], 0
	v_mfma_f32_16x16x32_bf16 v[2:5], v[174:177], v[216:219], 0
	v_mfma_f32_16x16x32_bf16 v[54:57], v[170:173], v[186:189], v[54:57]
	v_mfma_f32_16x16x32_bf16 v[46:49], v[178:181], v[186:189], v[46:49]
	v_mfma_f32_16x16x32_bf16 v[38:41], v[170:173], v[204:207], v[38:41]
	v_mfma_f32_16x16x32_bf16 v[30:33], v[178:181], v[204:207], v[30:33]
	v_mfma_f32_16x16x32_bf16 v[22:25], v[170:173], v[212:215], v[22:25]
	v_mfma_f32_16x16x32_bf16 v[14:17], v[178:181], v[212:215], v[14:17]
	v_mfma_f32_16x16x32_bf16 v[6:9], v[170:173], v[220:223], v[6:9]
	v_mfma_f32_16x16x32_bf16 v[2:5], v[178:181], v[220:223], v[2:5]
	s_setprio 0
	s_barrier
	s_nop 0
	s_add_i32 s70, 0, 0x18000
	s_add_i32 s71, 0, 0x1c000
	ds_read_b128 v[150:153], v253 offset:32768
	ds_read_b128 v[154:157], v253 offset:33792
	ds_read_b128 v[158:161], v253 offset:34816
	ds_read_b128 v[162:165], v253 offset:35840
	ds_read_b128 v[166:169], v253 offset:49152
	ds_read_b128 v[170:173], v253 offset:50176
	ds_read_b128 v[174:177], v253 offset:51200
	ds_read_b128 v[178:181], v253 offset:52224
	s_add_u32 s52, s52, 0x80000
	s_addc_u32 s53, s53, 0
	s_mov_b32 m0, s56
	ds_read_b128 v[182:185], v149 offset:32768
	ds_read_b128 v[186:189], v149 offset:33792
	ds_read_b128 v[190:193], v149 offset:34816
	ds_read_b128 v[204:207], v149 offset:35840
	ds_read_b128 v[208:211], v149 offset:36864
	ds_read_b128 v[212:215], v149 offset:37888
	ds_read_b128 v[216:219], v149 offset:38912
	ds_read_b128 v[220:223], v149 offset:39936
	global_load_lds_dwordx4 v130, s[52:53]
	s_mov_b32 m0, s57
	s_nop 0
	global_load_lds_dwordx4 v132, s[52:53]
	s_waitcnt vmcnt(8)
	s_waitcnt lgkmcnt(0)
	s_barrier
	s_setprio 1
	s_waitcnt lgkmcnt(0)
	v_mfma_f32_16x16x32_bf16 v[126:129], v[150:153], v[182:185], v[126:129]
	v_mfma_f32_16x16x32_bf16 v[122:125], v[158:161], v[182:185], v[122:125]
	v_mfma_f32_16x16x32_bf16 v[114:117], v[150:153], v[190:193], v[114:117]
	v_mfma_f32_16x16x32_bf16 v[106:109], v[158:161], v[190:193], v[106:109]
	v_mfma_f32_16x16x32_bf16 v[98:101], v[150:153], v[208:211], v[98:101]
	v_mfma_f32_16x16x32_bf16 v[90:93], v[158:161], v[208:211], v[90:93]
	v_mfma_f32_16x16x32_bf16 v[82:85], v[150:153], v[216:219], v[82:85]
	v_mfma_f32_16x16x32_bf16 v[74:77], v[158:161], v[216:219], v[74:77]
	v_mfma_f32_16x16x32_bf16 v[126:129], v[154:157], v[186:189], v[126:129]
	v_mfma_f32_16x16x32_bf16 v[122:125], v[162:165], v[186:189], v[122:125]
	v_mfma_f32_16x16x32_bf16 v[114:117], v[154:157], v[204:207], v[114:117]
	v_mfma_f32_16x16x32_bf16 v[106:109], v[162:165], v[204:207], v[106:109]
	v_mfma_f32_16x16x32_bf16 v[98:101], v[154:157], v[212:215], v[98:101]
	v_mfma_f32_16x16x32_bf16 v[90:93], v[162:165], v[212:215], v[90:93]
	v_mfma_f32_16x16x32_bf16 v[82:85], v[154:157], v[220:223], v[82:85]
	v_mfma_f32_16x16x32_bf16 v[74:77], v[162:165], v[220:223], v[74:77]
	s_setprio 0
	s_setprio 1
	v_mfma_f32_16x16x32_bf16 v[118:121], v[166:169], v[182:185], v[118:121]
	v_mfma_f32_16x16x32_bf16 v[110:113], v[174:177], v[182:185], v[110:113]
	v_mfma_f32_16x16x32_bf16 v[102:105], v[166:169], v[190:193], v[102:105]
	v_mfma_f32_16x16x32_bf16 v[94:97], v[174:177], v[190:193], v[94:97]
	v_mfma_f32_16x16x32_bf16 v[86:89], v[166:169], v[208:211], v[86:89]
	v_mfma_f32_16x16x32_bf16 v[78:81], v[174:177], v[208:211], v[78:81]
	v_mfma_f32_16x16x32_bf16 v[70:73], v[166:169], v[216:219], v[70:73]
	v_mfma_f32_16x16x32_bf16 v[66:69], v[174:177], v[216:219], v[66:69]
	v_mfma_f32_16x16x32_bf16 v[118:121], v[170:173], v[186:189], v[118:121]
	v_mfma_f32_16x16x32_bf16 v[110:113], v[178:181], v[186:189], v[110:113]
	v_mfma_f32_16x16x32_bf16 v[102:105], v[170:173], v[204:207], v[102:105]
	v_mfma_f32_16x16x32_bf16 v[94:97], v[178:181], v[204:207], v[94:97]
	v_mfma_f32_16x16x32_bf16 v[86:89], v[170:173], v[212:215], v[86:89]
	v_mfma_f32_16x16x32_bf16 v[78:81], v[178:181], v[212:215], v[78:81]
	v_mfma_f32_16x16x32_bf16 v[70:73], v[170:173], v[220:223], v[70:73]
	v_mfma_f32_16x16x32_bf16 v[66:69], v[178:181], v[220:223], v[66:69]
	s_setprio 0
	s_barrier
	s_add_u32 s100, s52, 0xfff80080
	s_addc_u32 s101, s53, -1
	s_add_u32 s98, s50, 0x80
	s_addc_u32 s99, s51, 0
	s_add_i32 s52, s70, s55
	s_mov_b32 m0, s52
	ds_read_b128 v[182:185], v149 offset:49152
	ds_read_b128 v[186:189], v149 offset:50176
	ds_read_b128 v[190:193], v149 offset:51200
	ds_read_b128 v[204:207], v149 offset:52224
	ds_read_b128 v[208:211], v149 offset:53248
	ds_read_b128 v[212:215], v149 offset:54272
	ds_read_b128 v[216:219], v149 offset:55296
	ds_read_b128 v[220:223], v149 offset:56320
	global_load_lds_dwordx4 v0, s[98:99]
	s_add_i32 m0, s52, 0x2000
	s_add_u32 s50, s50, 0x80080
	s_addc_u32 s51, s51, 0
	s_add_i32 s52, s71, s55
	global_load_lds_dwordx4 v134, s[98:99]
	s_mov_b32 m0, s52
	s_nop 0
	global_load_lds_dwordx4 v0, s[50:51]
	s_add_i32 m0, s52, 0x2000
	s_nop 0
	global_load_lds_dwordx4 v134, s[50:51]
	s_mov_b32 m0, s61
	s_nop 0
	global_load_lds_dwordx4 v130, s[100:101]
	s_mov_b32 m0, s62
	s_nop 0
	global_load_lds_dwordx4 v132, s[100:101]
	s_waitcnt vmcnt(8)
	s_waitcnt lgkmcnt(0)
	s_barrier
	s_setprio 1
	s_waitcnt lgkmcnt(0)
	v_mfma_f32_16x16x32_bf16 v[62:65], v[150:153], v[182:185], v[62:65]
	v_mfma_f32_16x16x32_bf16 v[58:61], v[158:161], v[182:185], v[58:61]
	v_mfma_f32_16x16x32_bf16 v[50:53], v[150:153], v[190:193], v[50:53]
	v_mfma_f32_16x16x32_bf16 v[42:45], v[158:161], v[190:193], v[42:45]
	v_mfma_f32_16x16x32_bf16 v[34:37], v[150:153], v[208:211], v[34:37]
	v_mfma_f32_16x16x32_bf16 v[26:29], v[158:161], v[208:211], v[26:29]
	v_mfma_f32_16x16x32_bf16 v[18:21], v[150:153], v[216:219], v[18:21]
	v_mfma_f32_16x16x32_bf16 v[10:13], v[158:161], v[216:219], v[10:13]
	v_mfma_f32_16x16x32_bf16 v[62:65], v[154:157], v[186:189], v[62:65]
	v_mfma_f32_16x16x32_bf16 v[58:61], v[162:165], v[186:189], v[58:61]
	v_mfma_f32_16x16x32_bf16 v[50:53], v[154:157], v[204:207], v[50:53]
	v_mfma_f32_16x16x32_bf16 v[42:45], v[162:165], v[204:207], v[42:45]
	v_mfma_f32_16x16x32_bf16 v[34:37], v[154:157], v[212:215], v[34:37]
	v_mfma_f32_16x16x32_bf16 v[26:29], v[162:165], v[212:215], v[26:29]
	v_mfma_f32_16x16x32_bf16 v[18:21], v[154:157], v[220:223], v[18:21]
	v_mfma_f32_16x16x32_bf16 v[10:13], v[162:165], v[220:223], v[10:13]
	s_setprio 0
	s_setprio 1
	v_mfma_f32_16x16x32_bf16 v[54:57], v[166:169], v[182:185], v[54:57]
	v_mfma_f32_16x16x32_bf16 v[46:49], v[174:177], v[182:185], v[46:49]
	v_mfma_f32_16x16x32_bf16 v[38:41], v[166:169], v[190:193], v[38:41]
	v_mfma_f32_16x16x32_bf16 v[30:33], v[174:177], v[190:193], v[30:33]
	v_mfma_f32_16x16x32_bf16 v[22:25], v[166:169], v[208:211], v[22:25]
	v_mfma_f32_16x16x32_bf16 v[14:17], v[174:177], v[208:211], v[14:17]
	v_mfma_f32_16x16x32_bf16 v[6:9], v[166:169], v[216:219], v[6:9]
	v_mfma_f32_16x16x32_bf16 v[2:5], v[174:177], v[216:219], v[2:5]
	v_mfma_f32_16x16x32_bf16 v[54:57], v[170:173], v[186:189], v[54:57]
	v_mfma_f32_16x16x32_bf16 v[46:49], v[178:181], v[186:189], v[46:49]
	v_mfma_f32_16x16x32_bf16 v[38:41], v[170:173], v[204:207], v[38:41]
	v_mfma_f32_16x16x32_bf16 v[30:33], v[178:181], v[204:207], v[30:33]
	v_mfma_f32_16x16x32_bf16 v[22:25], v[170:173], v[212:215], v[22:25]
	v_mfma_f32_16x16x32_bf16 v[14:17], v[178:181], v[212:215], v[14:17]
	v_mfma_f32_16x16x32_bf16 v[6:9], v[170:173], v[220:223], v[6:9]
	v_mfma_f32_16x16x32_bf16 v[2:5], v[178:181], v[220:223], v[2:5]
	s_setprio 0
	s_barrier
	s_add_u32 s42, s42, 0x100
	s_addc_u32 s43, s43, 0
	s_add_u32 s45, s45, 0x100
	s_addc_u32 s58, s58, 0
	s_cmp_ge_u32 s59, s33
	s_mov_b32 s50, s59
	s_cbranch_scc0 .LBB0_201
	s_branch .Lpeel_exit_0
